# P7: 4 consecutive tokens per wave share one union pass over selected blocks (all 16 MFMA columns used, per-lane token masks); block 0 kept in LDS
# speedup vs baseline: 1.0446x; 1.0446x over previous
.LBB0_745:
	s_barrier
	v_mbcnt_lo_u32_b32 v2, -1, 0
	v_mbcnt_hi_u32_b32 v2, -1, v2
	v_readlane_b32 s0, v235, 17
	s_lshl_b32 s0, s0, 6
	v_add_u32_e32 v2, s0, v2
	v_lshlrev_b32_e32 v2, 4, v2
	v_mov_b32_e32 v3, 0
	s_bfe_u32 s0, s96, 0x20001
	s_lshl_b32 s0, s0, 21
	v_readlane_b32 s2, v235, 48
	v_readlane_b32 s3, v235, 49
	v_readlane_b32 s4, v235, 46
	v_readlane_b32 s5, v235, 47
	s_add_u32 s2, s2, s0
	s_addc_u32 s3, s3, 0
	s_add_u32 s4, s4, s0
	s_addc_u32 s5, s5, 0
	v_lshl_add_u64 v[4:5], s[2:3], 0, v[2:3]
	v_lshl_add_u64 v[6:7], s[4:5], 0, v[2:3]
	global_load_dwordx4 v[8:11], v[4:5], off
	global_load_dwordx4 v[12:15], v[6:7], off
	s_waitcnt vmcnt(1)
	ds_write_b128 v2, v[8:11]
	s_waitcnt vmcnt(0)
	ds_write_b128 v2, v[12:15] offset:8192
	v_mbcnt_lo_u32_b32 v0, -1, 0
	v_mbcnt_hi_u32_b32 v0, -1, v0
	v_readlane_b32 s2, v234, 2
	v_add_u32_e32 v0, s78, v0
	v_ashrrev_i32_e32 v1, 31, v0
	v_readlane_b32 s3, v234, 3
	s_add_i32 s40, 0, 0x12000
	s_add_i32 s0, s78, 0x200
	v_lshl_add_u64 v[2:3], v[0:1], 2, s[2:3]
	global_load_dword v1, v[2:3], off
	v_lshl_add_u32 v0, v0, 2, s40
	s_waitcnt vmcnt(0)
	ds_write_b32 v0, v1
	v_mbcnt_lo_u32_b32 v0, -1, 0
	v_mbcnt_hi_u32_b32 v0, -1, v0
	s_nop 0
	v_add_u32_e32 v0, s0, v0
	v_ashrrev_i32_e32 v1, 31, v0
	v_lshl_add_u64 v[2:3], v[0:1], 2, s[2:3]
	global_load_dword v1, v[2:3], off
	v_lshl_add_u32 v0, v0, 2, s40
	s_add_i32 s0, s78, 0x400
	s_waitcnt vmcnt(0)
	ds_write_b32 v0, v1
	v_mbcnt_lo_u32_b32 v0, -1, 0
	v_mbcnt_hi_u32_b32 v0, -1, v0
	s_nop 0
	v_add_u32_e32 v0, s0, v0
	v_ashrrev_i32_e32 v1, 31, v0
	v_lshl_add_u64 v[2:3], v[0:1], 2, s[2:3]
	global_load_dword v1, v[2:3], off
	v_lshl_add_u32 v0, v0, 2, s40
	s_add_i32 s0, s78, 0x600
	s_waitcnt vmcnt(0)
	ds_write_b32 v0, v1
	v_mbcnt_lo_u32_b32 v0, -1, 0
	v_mbcnt_hi_u32_b32 v0, -1, v0
	s_nop 0
	v_add_u32_e32 v0, s0, v0
	v_ashrrev_i32_e32 v1, 31, v0
	v_lshl_add_u64 v[2:3], v[0:1], 2, s[2:3]
	global_load_dword v1, v[2:3], off
	v_lshl_add_u32 v0, v0, 2, s40
	s_add_i32 s0, s78, 0x800
	s_waitcnt vmcnt(0)
	ds_write_b32 v0, v1
	v_mbcnt_lo_u32_b32 v0, -1, 0
	v_mbcnt_hi_u32_b32 v0, -1, v0
	s_nop 0
	v_add_u32_e32 v0, s0, v0
	v_ashrrev_i32_e32 v1, 31, v0
	v_lshl_add_u64 v[2:3], v[0:1], 2, s[2:3]
	global_load_dword v1, v[2:3], off
	v_lshl_add_u32 v0, v0, 2, s40
	s_add_i32 s0, s78, 0xa00
	s_waitcnt vmcnt(0)
	ds_write_b32 v0, v1
	v_mbcnt_lo_u32_b32 v0, -1, 0
	v_mbcnt_hi_u32_b32 v0, -1, v0
	s_nop 0
	v_add_u32_e32 v0, s0, v0
	v_ashrrev_i32_e32 v1, 31, v0
	v_lshl_add_u64 v[2:3], v[0:1], 2, s[2:3]
	global_load_dword v1, v[2:3], off
	v_lshl_add_u32 v0, v0, 2, s40
	s_add_i32 s0, s78, 0xc00
	s_waitcnt vmcnt(0)
	ds_write_b32 v0, v1
	v_mbcnt_lo_u32_b32 v0, -1, 0
	v_mbcnt_hi_u32_b32 v0, -1, v0
	s_nop 0
	v_add_u32_e32 v0, s0, v0
	v_ashrrev_i32_e32 v1, 31, v0
	v_lshl_add_u64 v[2:3], v[0:1], 2, s[2:3]
	global_load_dword v1, v[2:3], off
	v_lshl_add_u32 v0, v0, 2, s40
	s_add_i32 s0, s78, 0xe00
	s_cmpk_lg_i32 s92, 0x100
	s_waitcnt vmcnt(0)
	ds_write_b32 v0, v1
	v_mbcnt_lo_u32_b32 v0, -1, 0
	v_mbcnt_hi_u32_b32 v0, -1, v0
	s_nop 0
	v_add_u32_e32 v0, s0, v0
	v_ashrrev_i32_e32 v1, 31, v0
	v_lshl_add_u64 v[2:3], v[0:1], 2, s[2:3]
	global_load_dword v1, v[2:3], off
	v_lshl_add_u32 v0, v0, 2, s40
	s_mov_b64 s[0:1], -1
	s_waitcnt vmcnt(0)
	ds_write_b32 v0, v1
	s_waitcnt lgkmcnt(0)
	s_barrier
	s_cbranch_scc0 .LBB0_779
	v_readlane_b32 s4, v235, 44
	s_cmp_gt_i32 s4, 0xffff
	v_readlane_b32 s5, v235, 45
	s_cbranch_scc1 .LBB0_778
	v_mov_b32_e32 v1, 0
	s_movk_i32 s1, 0x1000
	s_mov_b32 s0, 0x3d800000
	s_mov_b32 s33, 0xf149f2ca
	s_mov_b32 s41, 0xefa18f08
	s_mov_b32 s42, 0x3c800000
	s_movk_i32 s43, 0x2000
	v_mov_b32_e32 v118, 0x461c4000
	v_mov_b32_e32 v119, 0x1ff
	v_mov_b32_e32 v120, 0xf149f2ca
	s_branch .LBB0_749

.LBB0_782:
	s_lshl_b32 s1, s96, 13
	s_bfe_u32 s0, s96, 0x20001
	s_and_b32 s1, s1, 0x2000
	s_and_b32 s2, s96, -8
	s_lshl_b32 s2, s2, 2
	s_lshl_b32 s4, s0, 24
	s_lshl_b32 s41, s0, 21
	s_add_i32 s0, s1, s2
	v_readlane_b32 s1, v235, 17
	s_lshl_b32 s1, s1, 2
	s_lshl_b32 s3, s96, 12
	s_add_i32 s0, s0, s1
	s_bfe_u32 s9, s96, 0x10001
	s_and_b32 s3, s3, 0x4000
	s_ashr_i32 s1, s0, 31
	s_add_u32 s2, s0, s3
	s_addc_u32 s8, s1, 0
	v_readlane_b32 s5, v234, 7
	s_add_u32 s4, s5, s4
	v_readlane_b32 s5, v234, 8
	v_mbcnt_lo_u32_b32 v10, -1, 0
	v_mbcnt_hi_u32_b32 v10, -1, v10
	s_addc_u32 s5, s5, 0
	s_lshl_b64 s[6:7], s[0:1], 10
	v_lshlrev_b32_e32 v104, 2, v10
	v_lshlrev_b32_e32 v180, 4, v10
	v_bfe_u32 v232, v10, 2, 2
	v_mul_u32_u24_e32 v233, 0x4e00, v232
	s_add_u32 s6, s4, s6
	v_ashrrev_i32_e32 v105, 31, v104
	s_addc_u32 s7, s5, s7
	v_lshlrev_b64 v[2:3], 2, v[104:105]
	v_lshl_add_u64 v[0:1], s[6:7], 0, v[2:3]
	s_mulk_i32 s8, 0x4e00
	s_mul_hi_u32 s1, s2, 0x4e00
	v_lshlrev_b32_e32 v0, 8, v10
	s_add_i32 s1, s1, s8
	s_mulk_i32 s2, 0x4e00
	v_and_b32_e32 v0, 0x300, v0
	v_lshlrev_b32_e32 v1, 1, v10
	s_add_u32 s6, s94, s2
	v_lshl_or_b32 v4, s9, 10, v0
	v_add_u32_e32 v4, v4, v233
	v_mov_b32_e32 v0, 0
	v_and_b32_e32 v8, 0xffffffe0, v1
	s_addc_u32 s7, s95, s1
	v_mov_b32_e32 v5, v0
	v_ashrrev_i32_e32 v9, 31, v8
	v_lshl_add_u64 v[6:7], s[6:7], 0, v[4:5]
	v_lshlrev_b64 v[8:9], 1, v[8:9]
	v_lshl_add_u64 v[6:7], v[6:7], 0, v[8:9]
	global_load_dwordx4 v[36:39], v[6:7], off
	global_load_dwordx4 v[32:35], v[6:7], off offset:16
	global_load_dwordx4 v[28:31], v[6:7], off offset:32
	global_load_dwordx4 v[24:27], v[6:7], off offset:48
	v_lshl_add_u64 v[106:107], s[4:5], 0, v[2:3]
	v_lshl_add_u64 v[2:3], s[94:95], 0, v[4:5]
	v_lshl_add_u64 v[108:109], v[2:3], 0, v[8:9]
	v_lshlrev_b32_e32 v2, 4, v10
	v_readlane_b32 s10, v235, 48
	s_lshl_b32 s2, s9, 2
	v_ashrrev_i32_e32 v3, 31, v2
	v_readlane_b32 s11, v235, 49
	v_and_or_b32 v4, v10, 3, s2
	v_and_b32_e32 v1, 12, v10
	v_lshl_add_u64 v[112:113], s[10:11], 0, v[2:3]
	v_readlane_b32 s10, v235, 46
	v_lshl_add_u32 v154, v4, 11, s40
	v_readlane_b32 s11, v235, 47
	s_mov_b64 s[6:7], -1
	ds_read_b32 v110, v154 offset:2044
	v_lshl_add_u64 v[114:115], s[10:11], 0, v[2:3]
	v_mul_u32_u24_e32 v1, 3, v4
	v_readlane_b32 s10, v235, 21
	v_ashrrev_i32_e32 v5, 4, v10
	v_lshlrev_b32_e32 v2, 2, v1
	v_mov_b32_e32 v3, v0
	v_readlane_b32 s11, v235, 22
	v_lshlrev_b32_e32 v155, 3, v5
	v_sub_u32_e32 v155, v155, v232
	v_lshlrev_b32_e32 v124, 2, v5
	v_lshl_add_u32 v2, v232, 7, v2
	v_lshl_add_u64 v[122:123], s[10:11], 0, v[2:3]
	v_lshlrev_b32_e32 v2, 7, v4
	v_lshlrev_b32_e32 v4, 8, v4
	v_mov_b32_e32 v5, v0
	v_ashrrev_i32_e32 v125, 31, v124
	v_lshl_add_u32 v4, v232, 11, v4
	v_lshl_add_u64 v[4:5], s[72:73], 0, v[4:5]
	v_lshl_add_u64 v[126:127], v[124:125], 1, v[4:5]
	s_movk_i32 s1, 0x2000
	s_mov_b32 s8, 0
	v_cmp_ne_u32_e64 s[4:5], 0, v10
	v_or_b32_e32 v121, 1, v104
	v_or_b32_e32 v152, 2, v104
	v_or_b32_e32 v153, 3, v104
	v_not_b32_e32 v156, v155
	v_add_u32_e32 v105, 3, v155
	v_add_u32_e32 v116, 2, v155
	v_add_u32_e32 v117, 5, v155
	v_add_u32_e32 v118, 4, v155
	v_add_u32_e32 v119, 7, v155
	v_add_u32_e32 v120, 6, v155
	s_waitcnt lgkmcnt(0)
	v_mov_b32_e32 v111, v110
	s_movk_i32 s33, 0x1000
	s_mov_b32 s2, 0x3d800000
	s_mov_b32 s40, 0xf149f2ca
	s_mov_b32 s42, 0xefa18f08
	s_mov_b32 s43, 0x3c800000
	v_lshlrev_b32_e32 v128, 1, v2
	v_add_u32_e32 v128, v128, v233
	s_mov_b64 s[30:31], 0x2400
	v_mov_b32_e32 v157, 0x4e00
	v_mov_b32_e32 v158, 0x461c4000
	v_mov_b32_e32 v159, 0x1ff
	v_mov_b32_e32 v160, 0xf149f2ca
	s_ashr_i32 s11, s0, 31
	s_mov_b32 s10, s0
	s_lshl_b64 s[10:11], s[10:11], 10
	v_lshl_add_u64 v[2:3], v[106:107], 0, s[10:11]
	global_load_dwordx4 v[4:7], v[2:3], off offset:1024
	global_load_dwordx4 v[176:179], v[2:3], off offset:2048
	global_load_dwordx4 v[252:255], v[2:3], off offset:3072
	s_waitcnt vmcnt(0)
	s_branch .LBB0_784
.LBB0_783:
	s_or_b64 exec, exec, s[8:9]
	s_cmp_eq_u32 s44, 8
	s_mov_b32 s8, s44
	s_waitcnt vmcnt(3)
	v_mov_b32_e32 v36, v8
	v_mov_b32_e32 v37, v9
	v_mov_b32_e32 v38, v10
	v_mov_b32_e32 v39, v11
	s_waitcnt vmcnt(2)
	v_mov_b32_e32 v32, v12
	v_mov_b32_e32 v33, v13
	v_mov_b32_e32 v34, v14
	v_mov_b32_e32 v35, v15
	s_waitcnt vmcnt(1)
	v_mov_b32_e32 v28, v16
	v_mov_b32_e32 v29, v17
	v_mov_b32_e32 v30, v18
	v_mov_b32_e32 v31, v19
	s_waitcnt vmcnt(0)
	v_mov_b32_e32 v24, v20
	v_mov_b32_e32 v25, v21
	v_mov_b32_e32 v26, v22
	v_mov_b32_e32 v27, v23
	s_cbranch_scc1 .LBB0_815
.LBB0_784:
	s_add_i32 s44, s8, 1
	s_cmp_eq_u32 s8, 7
	v_mov_b32_e32 v8, v36
	v_mov_b32_e32 v9, v37
	v_mov_b32_e32 v10, v38
	v_mov_b32_e32 v11, v39
	v_mov_b32_e32 v12, v32
	v_mov_b32_e32 v13, v33
	v_mov_b32_e32 v14, v34
	v_mov_b32_e32 v15, v35
	v_mov_b32_e32 v16, v28
	v_mov_b32_e32 v17, v29
	v_mov_b32_e32 v18, v30
	v_mov_b32_e32 v19, v31
	v_mov_b32_e32 v20, v24
	v_mov_b32_e32 v21, v25
	v_mov_b32_e32 v22, v26
	v_mov_b32_e32 v23, v27
	s_cbranch_scc1 .LBB0_786
	s_lshl_b32 s9, s44, 10
	s_add_i32 s10, s0, s9
	s_ashr_i32 s11, s10, 31
	s_add_u32 s9, s10, s3
	s_addc_u32 s12, s11, 0
	s_mulk_i32 s12, 0x4e00
	v_mad_u64_u32 v[2:3], s[10:11], s9, v157, v[108:109]
	v_add_u32_e32 v3, s12, v3
	global_load_dwordx4 v[8:11], v[2:3], off
	global_load_dwordx4 v[12:15], v[2:3], off offset:16
	global_load_dwordx4 v[16:19], v[2:3], off offset:32
	global_load_dwordx4 v[20:23], v[2:3], off offset:48
.LBB0_786:
	s_lshl_b32 s8, s8, 10
	s_add_i32 s45, s0, s8
	s_ashr_i32 s11, s45, 31
	s_mov_b32 s10, s45
	s_lshl_b64 s[10:11], s[10:11], 10
	v_lshl_add_u64 v[2:3], v[106:107], 0, s[10:11]
	global_load_dwordx4 v[40:43], v[2:3], off
	s_ashr_i32 s18, s45, 6
	v_cmp_gt_i32_e64 s[10:11], s18, v104
	s_mov_b64 s[16:17], -1
	s_cmp_lt_i32 s18, 16
	v_cmp_ge_i32_e64 s[14:15], s18, v104
	v_cmp_ge_i32_e64 s[12:13], s18, v152
	v_cmp_ge_i32_e64 s[8:9], s18, v153
	s_cbranch_scc1 .Lx798_c1
	s_add_i32 s18, s18, -1
	v_cmp_gt_i32_e32 vcc, s18, v104
	s_and_b64 vcc, s[4:5], vcc
	s_nop 0
	v_cndmask_b32_e32 v1, v158, v4, vcc
	v_cmp_gt_i32_e32 vcc, s18, v121
	v_cndmask_b32_e64 v3, -1.0, v1, s[14:15]
	s_nop 0
	v_cndmask_b32_e32 v1, v158, v5, vcc
	v_cmp_gt_i32_e32 vcc, s18, v152
	v_cndmask_b32_e64 v4, -1.0, v1, s[10:11]
	v_mov_b32_e32 v5, 0
	v_cndmask_b32_e32 v1, v158, v6, vcc
	v_cmp_gt_i32_e32 vcc, s18, v153
	v_cndmask_b32_e64 v1, -1.0, v1, s[12:13]
	v_mov_b32_e32 v6, 30
	v_cndmask_b32_e32 v2, v158, v7, vcc
	v_cndmask_b32_e64 v2, -1.0, v2, s[8:9]
.Lx788_c1:
	v_lshlrev_b32_e64 v7, v6, 1
	v_or_b32_e32 v7, v7, v5
	v_cmp_ge_f32_e64 s[16:17], v3, v7
	v_cmp_ge_f32_e64 s[18:19], v4, v7
	v_cmp_ge_f32_e64 s[20:21], v1, v7
	s_bcnt1_i32_b64 s16, s[16:17]
	s_bcnt1_i32_b64 s17, s[18:19]
	v_cmp_ge_f32_e64 s[22:23], v2, v7
	s_bcnt1_i32_b64 s18, s[20:21]
	s_add_i32 s16, s17, s16
	s_bcnt1_i32_b64 s19, s[22:23]
	s_add_i32 s16, s16, s18
	s_add_i32 s18, s16, s19
	s_cmp_gt_u32 s18, 15
	s_cselect_b64 s[16:17], -1, 0
	s_cmp_eq_u32 s18, 16
	v_subrev_co_u32_e32 v6, vcc, 1, v6
	s_cselect_b64 s[18:19], -1, 0
	s_or_b64 s[18:19], s[18:19], vcc
	s_andn2_b64 vcc, exec, s[18:19]
	v_cndmask_b32_e64 v5, v5, v7, s[16:17]
	s_cbranch_vccnz .Lx788_c1
	v_cmp_gt_f32_e32 vcc, v3, v5
	s_bcnt1_i32_b64 s34, vcc
	v_cmp_gt_f32_e32 vcc, v4, v5
	s_bcnt1_i32_b64 s35, vcc
	v_cmp_gt_f32_e32 vcc, v1, v5
	v_cmp_gt_f32_e64 s[16:17], v2, v5
	v_cmp_eq_f32_e64 s[26:27], v3, v5
	v_cmp_eq_f32_e64 s[24:25], v4, v5
	v_cmp_ngt_f32_e64 s[28:29], v3, v5
	v_cmp_ngt_f32_e64 s[22:23], v4, v5
	s_bcnt1_i32_b64 s36, vcc
	s_bcnt1_i32_b64 s37, s[16:17]
	v_mbcnt_lo_u32_b32 v3, s26, 0
	v_mbcnt_lo_u32_b32 v4, s24, 0
	v_cmp_eq_f32_e64 s[16:17], v1, v5
	v_cmp_eq_f32_e64 s[18:19], v2, v5
	s_add_i32 s34, s34, s35
	v_cmp_ngt_f32_e64 s[20:21], v1, v5
	v_cmp_ngt_f32_e32 vcc, v2, v5
	v_mbcnt_hi_u32_b32 v3, s27, v3
	v_mbcnt_hi_u32_b32 v4, s25, v4
	v_mbcnt_lo_u32_b32 v1, s16, 0
	v_mbcnt_lo_u32_b32 v2, s18, 0
	s_add_i32 s34, s34, s36
	v_add_u32_e32 v3, v4, v3
	v_mbcnt_hi_u32_b32 v1, s17, v1
	v_mbcnt_hi_u32_b32 v2, s19, v2
	s_add_i32 s34, s34, s37
	v_add3_u32 v1, v3, v1, v2
	s_sub_i32 s46, 16, s34
	s_mov_b64 s[34:35], -1
	s_mov_b64 s[36:37], -1
	s_and_saveexec_b64 s[38:39], s[28:29]
	v_cmp_gt_i32_e64 s[28:29], s46, v1
	s_and_b64 s[28:29], s[26:27], s[28:29]
	s_orn2_b64 s[36:37], s[28:29], exec
	s_or_b64 exec, exec, s[38:39]
	v_cndmask_b32_e64 v2, 0, 1, s[26:27]
	v_add_u32_e32 v1, v1, v2
	s_and_saveexec_b64 s[26:27], s[22:23]
	v_cmp_gt_i32_e64 s[22:23], s46, v1
	s_and_b64 s[22:23], s[24:25], s[22:23]
	s_orn2_b64 s[34:35], s[22:23], exec
	s_or_b64 exec, exec, s[26:27]
	v_cndmask_b32_e64 v2, 0, 1, s[24:25]
	v_add_u32_e32 v1, v1, v2
	s_mov_b64 s[22:23], -1
	s_mov_b64 s[24:25], -1
	s_and_saveexec_b64 s[26:27], s[20:21]
	v_cmp_gt_i32_e64 s[20:21], s46, v1
	s_and_b64 s[20:21], s[16:17], s[20:21]
	s_orn2_b64 s[24:25], s[20:21], exec
	s_or_b64 exec, exec, s[26:27]
	s_and_saveexec_b64 s[20:21], vcc
	v_cndmask_b32_e64 v2, 0, 1, s[16:17]
	v_add_u32_e32 v1, v1, v2
	v_cmp_gt_i32_e32 vcc, s46, v1
	s_and_b64 s[16:17], s[18:19], vcc
	s_orn2_b64 s[22:23], s[16:17], exec
	s_or_b64 exec, exec, s[20:21]
	s_mov_b64 s[16:17], 0

.Lx800_c1:
	v_cndmask_b32_e64 v1, 0, 1, s[36:37]
	v_cndmask_b32_e64 v2, 0, 1, s[34:35]
	v_cndmask_b32_e64 v3, 0, 1, s[24:25]
	v_cndmask_b32_e64 v4, 0, 1, s[22:23]
	v_cmp_ne_u32_e64 s[12:13], 0, v1
	v_cmp_ne_u32_e64 s[14:15], 0, v2
	v_cmp_ne_u32_e64 s[8:9], 0, v3
	v_cmp_ne_u32_e64 s[10:11], 0, v4
	s_nop 1
	s_mov_b64 s[62:63], s[12:13]
	s_mov_b64 s[64:65], s[14:15]
	s_mov_b64 s[66:67], s[8:9]
	s_mov_b64 s[68:69], s[10:11]
	v_writelane_b32 v181, s12, 8
	v_writelane_b32 v181, s13, 9
	v_writelane_b32 v181, s14, 10
	v_writelane_b32 v181, s15, 11
	v_writelane_b32 v181, s8, 12
	v_writelane_b32 v181, s9, 13
	v_writelane_b32 v181, s10, 14
	v_writelane_b32 v181, s11, 15
	s_ashr_i32 s18, s45, 6
	v_cmp_gt_i32_e64 s[10:11], s18, v104
	s_mov_b64 s[16:17], -1
	s_cmp_lt_i32 s18, 16
	v_cmp_ge_i32_e64 s[14:15], s18, v104
	v_cmp_ge_i32_e64 s[12:13], s18, v152
	v_cmp_ge_i32_e64 s[8:9], s18, v153
	s_cbranch_scc1 .Lx798_c2
	s_add_i32 s18, s18, -1
	v_cmp_gt_i32_e32 vcc, s18, v104
	s_and_b64 vcc, s[4:5], vcc
	s_nop 0
	v_cndmask_b32_e32 v1, v158, v176, vcc
	v_cmp_gt_i32_e32 vcc, s18, v121
	v_cndmask_b32_e64 v3, -1.0, v1, s[14:15]
	s_nop 0
	v_cndmask_b32_e32 v1, v158, v177, vcc
	v_cmp_gt_i32_e32 vcc, s18, v152
	v_cndmask_b32_e64 v176, -1.0, v1, s[10:11]
	v_mov_b32_e32 v177, 0
	v_cndmask_b32_e32 v1, v158, v178, vcc
	v_cmp_gt_i32_e32 vcc, s18, v153
	v_cndmask_b32_e64 v1, -1.0, v1, s[12:13]
	v_mov_b32_e32 v178, 30
	v_cndmask_b32_e32 v2, v158, v179, vcc
	v_cndmask_b32_e64 v2, -1.0, v2, s[8:9]
.Lx788_c2:
	v_lshlrev_b32_e64 v179, v178, 1
	v_or_b32_e32 v179, v179, v177
	v_cmp_ge_f32_e64 s[16:17], v3, v179
	v_cmp_ge_f32_e64 s[18:19], v176, v179
	v_cmp_ge_f32_e64 s[20:21], v1, v179
	s_bcnt1_i32_b64 s16, s[16:17]
	s_bcnt1_i32_b64 s17, s[18:19]
	v_cmp_ge_f32_e64 s[22:23], v2, v179
	s_bcnt1_i32_b64 s18, s[20:21]
	s_add_i32 s16, s17, s16
	s_bcnt1_i32_b64 s19, s[22:23]
	s_add_i32 s16, s16, s18
	s_add_i32 s18, s16, s19
	s_cmp_gt_u32 s18, 15
	s_cselect_b64 s[16:17], -1, 0
	s_cmp_eq_u32 s18, 16
	v_subrev_co_u32_e32 v178, vcc, 1, v178
	s_cselect_b64 s[18:19], -1, 0
	s_or_b64 s[18:19], s[18:19], vcc
	s_andn2_b64 vcc, exec, s[18:19]
	v_cndmask_b32_e64 v177, v177, v179, s[16:17]
	s_cbranch_vccnz .Lx788_c2
	v_cmp_gt_f32_e32 vcc, v3, v177
	s_bcnt1_i32_b64 s34, vcc
	v_cmp_gt_f32_e32 vcc, v176, v177
	s_bcnt1_i32_b64 s35, vcc
	v_cmp_gt_f32_e32 vcc, v1, v177
	v_cmp_gt_f32_e64 s[16:17], v2, v177
	v_cmp_eq_f32_e64 s[26:27], v3, v177
	v_cmp_eq_f32_e64 s[24:25], v176, v177
	v_cmp_ngt_f32_e64 s[28:29], v3, v177
	v_cmp_ngt_f32_e64 s[22:23], v176, v177
	s_bcnt1_i32_b64 s36, vcc
	s_bcnt1_i32_b64 s37, s[16:17]
	v_mbcnt_lo_u32_b32 v3, s26, 0
	v_mbcnt_lo_u32_b32 v176, s24, 0
	v_cmp_eq_f32_e64 s[16:17], v1, v177
	v_cmp_eq_f32_e64 s[18:19], v2, v177
	s_add_i32 s34, s34, s35
	v_cmp_ngt_f32_e64 s[20:21], v1, v177
	v_cmp_ngt_f32_e32 vcc, v2, v177
	v_mbcnt_hi_u32_b32 v3, s27, v3
	v_mbcnt_hi_u32_b32 v176, s25, v176
	v_mbcnt_lo_u32_b32 v1, s16, 0
	v_mbcnt_lo_u32_b32 v2, s18, 0
	s_add_i32 s34, s34, s36
	v_add_u32_e32 v3, v176, v3
	v_mbcnt_hi_u32_b32 v1, s17, v1
	v_mbcnt_hi_u32_b32 v2, s19, v2
	s_add_i32 s34, s34, s37
	v_add3_u32 v1, v3, v1, v2
	s_sub_i32 s46, 16, s34
	s_mov_b64 s[34:35], -1
	s_mov_b64 s[36:37], -1
	s_and_saveexec_b64 s[38:39], s[28:29]
	v_cmp_gt_i32_e64 s[28:29], s46, v1
	s_and_b64 s[28:29], s[26:27], s[28:29]
	s_orn2_b64 s[36:37], s[28:29], exec
	s_or_b64 exec, exec, s[38:39]
	v_cndmask_b32_e64 v2, 0, 1, s[26:27]
	v_add_u32_e32 v1, v1, v2
	s_and_saveexec_b64 s[26:27], s[22:23]
	v_cmp_gt_i32_e64 s[22:23], s46, v1
	s_and_b64 s[22:23], s[24:25], s[22:23]
	s_orn2_b64 s[34:35], s[22:23], exec
	s_or_b64 exec, exec, s[26:27]
	v_cndmask_b32_e64 v2, 0, 1, s[24:25]
	v_add_u32_e32 v1, v1, v2
	s_mov_b64 s[22:23], -1
	s_mov_b64 s[24:25], -1
	s_and_saveexec_b64 s[26:27], s[20:21]
	v_cmp_gt_i32_e64 s[20:21], s46, v1
	s_and_b64 s[20:21], s[16:17], s[20:21]
	s_orn2_b64 s[24:25], s[20:21], exec
	s_or_b64 exec, exec, s[26:27]
	s_and_saveexec_b64 s[20:21], vcc
	v_cndmask_b32_e64 v2, 0, 1, s[16:17]
	v_add_u32_e32 v1, v1, v2
	v_cmp_gt_i32_e32 vcc, s46, v1
	s_and_b64 s[16:17], s[18:19], vcc
	s_orn2_b64 s[22:23], s[16:17], exec
	s_or_b64 exec, exec, s[20:21]
	s_mov_b64 s[16:17], 0

.Lx800_c2:
	v_cndmask_b32_e64 v1, 0, 1, s[36:37]
	v_cndmask_b32_e64 v2, 0, 1, s[34:35]
	v_cndmask_b32_e64 v3, 0, 1, s[24:25]
	v_cndmask_b32_e64 v176, 0, 1, s[22:23]
	v_cmp_ne_u32_e64 s[12:13], 0, v1
	v_cmp_ne_u32_e64 s[14:15], 0, v2
	v_cmp_ne_u32_e64 s[8:9], 0, v3
	v_cmp_ne_u32_e64 s[10:11], 0, v176
	s_nop 1
	s_or_b64 s[62:63], s[62:63], s[12:13]
	s_or_b64 s[64:65], s[64:65], s[14:15]
	s_or_b64 s[66:67], s[66:67], s[8:9]
	s_or_b64 s[68:69], s[68:69], s[10:11]
	v_writelane_b32 v181, s12, 16
	v_writelane_b32 v181, s13, 17
	v_writelane_b32 v181, s14, 18
	v_writelane_b32 v181, s15, 19
	v_writelane_b32 v181, s8, 20
	v_writelane_b32 v181, s9, 21
	v_writelane_b32 v181, s10, 22
	v_writelane_b32 v181, s11, 23
	s_ashr_i32 s18, s45, 6
	v_cmp_gt_i32_e64 s[10:11], s18, v104
	s_mov_b64 s[16:17], -1
	s_cmp_lt_i32 s18, 16
	v_cmp_ge_i32_e64 s[14:15], s18, v104
	v_cmp_ge_i32_e64 s[12:13], s18, v152
	v_cmp_ge_i32_e64 s[8:9], s18, v153
	s_cbranch_scc1 .Lx798_c3
	s_add_i32 s18, s18, -1
	v_cmp_gt_i32_e32 vcc, s18, v104
	s_and_b64 vcc, s[4:5], vcc
	s_nop 0
	v_cndmask_b32_e32 v1, v158, v252, vcc
	v_cmp_gt_i32_e32 vcc, s18, v121
	v_cndmask_b32_e64 v3, -1.0, v1, s[14:15]
	s_nop 0
	v_cndmask_b32_e32 v1, v158, v253, vcc
	v_cmp_gt_i32_e32 vcc, s18, v152
	v_cndmask_b32_e64 v252, -1.0, v1, s[10:11]
	v_mov_b32_e32 v253, 0
	v_cndmask_b32_e32 v1, v158, v254, vcc
	v_cmp_gt_i32_e32 vcc, s18, v153
	v_cndmask_b32_e64 v1, -1.0, v1, s[12:13]
	v_mov_b32_e32 v254, 30
	v_cndmask_b32_e32 v2, v158, v255, vcc
	v_cndmask_b32_e64 v2, -1.0, v2, s[8:9]
.Lx788_c3:
	v_lshlrev_b32_e64 v255, v254, 1
	v_or_b32_e32 v255, v255, v253
	v_cmp_ge_f32_e64 s[16:17], v3, v255
	v_cmp_ge_f32_e64 s[18:19], v252, v255
	v_cmp_ge_f32_e64 s[20:21], v1, v255
	s_bcnt1_i32_b64 s16, s[16:17]
	s_bcnt1_i32_b64 s17, s[18:19]
	v_cmp_ge_f32_e64 s[22:23], v2, v255
	s_bcnt1_i32_b64 s18, s[20:21]
	s_add_i32 s16, s17, s16
	s_bcnt1_i32_b64 s19, s[22:23]
	s_add_i32 s16, s16, s18
	s_add_i32 s18, s16, s19
	s_cmp_gt_u32 s18, 15
	s_cselect_b64 s[16:17], -1, 0
	s_cmp_eq_u32 s18, 16
	v_subrev_co_u32_e32 v254, vcc, 1, v254
	s_cselect_b64 s[18:19], -1, 0
	s_or_b64 s[18:19], s[18:19], vcc
	s_andn2_b64 vcc, exec, s[18:19]
	v_cndmask_b32_e64 v253, v253, v255, s[16:17]
	s_cbranch_vccnz .Lx788_c3
	v_cmp_gt_f32_e32 vcc, v3, v253
	s_bcnt1_i32_b64 s34, vcc
	v_cmp_gt_f32_e32 vcc, v252, v253
	s_bcnt1_i32_b64 s35, vcc
	v_cmp_gt_f32_e32 vcc, v1, v253
	v_cmp_gt_f32_e64 s[16:17], v2, v253
	v_cmp_eq_f32_e64 s[26:27], v3, v253
	v_cmp_eq_f32_e64 s[24:25], v252, v253
	v_cmp_ngt_f32_e64 s[28:29], v3, v253
	v_cmp_ngt_f32_e64 s[22:23], v252, v253
	s_bcnt1_i32_b64 s36, vcc
	s_bcnt1_i32_b64 s37, s[16:17]
	v_mbcnt_lo_u32_b32 v3, s26, 0
	v_mbcnt_lo_u32_b32 v252, s24, 0
	v_cmp_eq_f32_e64 s[16:17], v1, v253
	v_cmp_eq_f32_e64 s[18:19], v2, v253
	s_add_i32 s34, s34, s35
	v_cmp_ngt_f32_e64 s[20:21], v1, v253
	v_cmp_ngt_f32_e32 vcc, v2, v253
	v_mbcnt_hi_u32_b32 v3, s27, v3
	v_mbcnt_hi_u32_b32 v252, s25, v252
	v_mbcnt_lo_u32_b32 v1, s16, 0
	v_mbcnt_lo_u32_b32 v2, s18, 0
	s_add_i32 s34, s34, s36
	v_add_u32_e32 v3, v252, v3
	v_mbcnt_hi_u32_b32 v1, s17, v1
	v_mbcnt_hi_u32_b32 v2, s19, v2
	s_add_i32 s34, s34, s37
	v_add3_u32 v1, v3, v1, v2
	s_sub_i32 s46, 16, s34
	s_mov_b64 s[34:35], -1
	s_mov_b64 s[36:37], -1
	s_and_saveexec_b64 s[38:39], s[28:29]
	v_cmp_gt_i32_e64 s[28:29], s46, v1
	s_and_b64 s[28:29], s[26:27], s[28:29]
	s_orn2_b64 s[36:37], s[28:29], exec
	s_or_b64 exec, exec, s[38:39]
	v_cndmask_b32_e64 v2, 0, 1, s[26:27]
	v_add_u32_e32 v1, v1, v2
	s_and_saveexec_b64 s[26:27], s[22:23]
	v_cmp_gt_i32_e64 s[22:23], s46, v1
	s_and_b64 s[22:23], s[24:25], s[22:23]
	s_orn2_b64 s[34:35], s[22:23], exec
	s_or_b64 exec, exec, s[26:27]
	v_cndmask_b32_e64 v2, 0, 1, s[24:25]
	v_add_u32_e32 v1, v1, v2
	s_mov_b64 s[22:23], -1
	s_mov_b64 s[24:25], -1
	s_and_saveexec_b64 s[26:27], s[20:21]
	v_cmp_gt_i32_e64 s[20:21], s46, v1
	s_and_b64 s[20:21], s[16:17], s[20:21]
	s_orn2_b64 s[24:25], s[20:21], exec
	s_or_b64 exec, exec, s[26:27]
	s_and_saveexec_b64 s[20:21], vcc
	v_cndmask_b32_e64 v2, 0, 1, s[16:17]
	v_add_u32_e32 v1, v1, v2
	v_cmp_gt_i32_e32 vcc, s46, v1
	s_and_b64 s[16:17], s[18:19], vcc
	s_orn2_b64 s[22:23], s[16:17], exec
	s_or_b64 exec, exec, s[20:21]
	s_mov_b64 s[16:17], 0

.Lx800_c3:
	v_cndmask_b32_e64 v1, 0, 1, s[36:37]
	v_cndmask_b32_e64 v2, 0, 1, s[34:35]
	v_cndmask_b32_e64 v3, 0, 1, s[24:25]
	v_cndmask_b32_e64 v252, 0, 1, s[22:23]
	v_cmp_ne_u32_e64 s[12:13], 0, v1
	v_cmp_ne_u32_e64 s[14:15], 0, v2
	v_cmp_ne_u32_e64 s[8:9], 0, v3
	v_cmp_ne_u32_e64 s[10:11], 0, v252
	s_nop 1
	s_or_b64 s[62:63], s[62:63], s[12:13]
	s_or_b64 s[64:65], s[64:65], s[14:15]
	s_or_b64 s[66:67], s[66:67], s[8:9]
	s_or_b64 s[68:69], s[68:69], s[10:11]
	v_writelane_b32 v181, s12, 24
	v_writelane_b32 v181, s13, 25
	v_writelane_b32 v181, s14, 26
	v_writelane_b32 v181, s15, 27
	v_writelane_b32 v181, s8, 28
	v_writelane_b32 v181, s9, 29
	v_writelane_b32 v181, s10, 30
	v_writelane_b32 v181, s11, 31
	s_waitcnt vmcnt(0)
	s_ashr_i32 s18, s45, 6
	v_cmp_gt_i32_e64 s[10:11], s18, v104
	s_mov_b64 s[16:17], -1
	s_cmp_lt_i32 s18, 16
	v_cmp_ge_i32_e64 s[14:15], s18, v104
	v_cmp_ge_i32_e64 s[12:13], s18, v152
	v_cmp_ge_i32_e64 s[8:9], s18, v153
	s_cbranch_scc1 .Lx798_c0
	s_add_i32 s18, s18, -1
	v_cmp_gt_i32_e32 vcc, s18, v104
	s_and_b64 vcc, s[4:5], vcc
	s_nop 0
	v_cndmask_b32_e32 v1, v158, v40, vcc
	v_cmp_gt_i32_e32 vcc, s18, v121
	v_cndmask_b32_e64 v3, -1.0, v1, s[14:15]
	s_nop 0
	v_cndmask_b32_e32 v1, v158, v41, vcc
	v_cmp_gt_i32_e32 vcc, s18, v152
	v_cndmask_b32_e64 v40, -1.0, v1, s[10:11]
	v_mov_b32_e32 v41, 0
	v_cndmask_b32_e32 v1, v158, v42, vcc
	v_cmp_gt_i32_e32 vcc, s18, v153
	v_cndmask_b32_e64 v1, -1.0, v1, s[12:13]
	v_mov_b32_e32 v42, 30
	v_cndmask_b32_e32 v2, v158, v43, vcc
	v_cndmask_b32_e64 v2, -1.0, v2, s[8:9]

.Lx800_c0:
	v_cndmask_b32_e64 v1, 0, 1, s[36:37]
	v_cndmask_b32_e64 v2, 0, 1, s[34:35]
	v_cndmask_b32_e64 v3, 0, 1, s[24:25]
	v_cndmask_b32_e64 v40, 0, 1, s[22:23]
	v_cmp_ne_u32_e64 s[12:13], 0, v1
	v_cmp_ne_u32_e64 s[14:15], 0, v2
	v_cmp_ne_u32_e64 s[8:9], 0, v3
	v_cmp_ne_u32_e64 s[10:11], 0, v40
	s_nop 1
	s_or_b64 s[62:63], s[62:63], s[12:13]
	s_or_b64 s[64:65], s[64:65], s[14:15]
	s_or_b64 s[66:67], s[66:67], s[8:9]
	s_or_b64 s[68:69], s[68:69], s[10:11]
	v_writelane_b32 v181, s12, 0
	v_writelane_b32 v181, s13, 1
	v_writelane_b32 v181, s14, 2
	v_writelane_b32 v181, s15, 3
	v_writelane_b32 v181, s8, 4
	v_writelane_b32 v181, s9, 5
	v_writelane_b32 v181, s10, 6
	v_writelane_b32 v181, s11, 7
	s_cmp_eq_u32 s44, 8
	s_cbranch_scc1 .Lx_noimp
	s_lshl_b32 s9, s44, 10
	s_add_i32 s10, s0, s9
	s_ashr_i32 s11, s10, 31
	s_lshl_b64 s[10:11], s[10:11], 10
	v_lshl_add_u64 v[2:3], v[106:107], 0, s[10:11]
	global_load_dwordx4 v[4:7], v[2:3], off offset:1024
	global_load_dwordx4 v[176:179], v[2:3], off offset:2048
	global_load_dwordx4 v[252:255], v[2:3], off offset:3072
.Lx_noimp:
	v_lshlrev_b32_e32 v1, 16, v36
	v_and_b32_e32 v2, 0xffff0000, v36
	v_mul_f32_e32 v1, 0x41800000, v1
	v_mul_f32_e32 v2, 0x41800000, v2
	v_mov_b32_e32 v36, 0
	v_cvt_pk_fp8_f32 v36, v1, v2
	v_lshlrev_b32_e32 v3, 16, v37
	v_and_b32_e32 v2, 0xffff0000, v37
	v_mul_f32_e32 v1, 0x41800000, v3
	v_mul_f32_e32 v2, 0x41800000, v2
	v_cvt_pk_fp8_f32 v36, v1, v2 op_sel:[0,0,1]
	v_lshlrev_b32_e32 v1, 16, v38
	v_and_b32_e32 v2, 0xffff0000, v38
	v_mul_f32_e32 v1, 0x41800000, v1
	v_mul_f32_e32 v2, 0x41800000, v2
	v_mov_b32_e32 v37, 0
	v_cvt_pk_fp8_f32 v37, v1, v2
	v_lshlrev_b32_e32 v3, 16, v39
	v_and_b32_e32 v2, 0xffff0000, v39
	v_mul_f32_e32 v1, 0x41800000, v3
	v_mul_f32_e32 v2, 0x41800000, v2
	v_cvt_pk_fp8_f32 v37, v1, v2 op_sel:[0,0,1]
	v_lshlrev_b32_e32 v1, 16, v32
	v_and_b32_e32 v2, 0xffff0000, v32
	v_mul_f32_e32 v1, 0x41800000, v1
	v_mul_f32_e32 v2, 0x41800000, v2
	v_lshlrev_b32_e32 v3, 16, v33
	v_and_b32_e32 v32, 0xffff0000, v33
	v_mov_b32_e32 v33, 0
	v_cvt_pk_fp8_f32 v33, v1, v2
	v_lshlrev_b32_e32 v1, 16, v34
	v_and_b32_e32 v2, 0xffff0000, v34
	v_mul_f32_e32 v1, 0x41800000, v1
	v_mul_f32_e32 v2, 0x41800000, v2
	v_mov_b32_e32 v38, 0
	v_cvt_pk_fp8_f32 v38, v1, v2
	v_lshlrev_b32_e32 v34, 16, v35
	v_and_b32_e32 v2, 0xffff0000, v35
	v_mul_f32_e32 v1, 0x41800000, v34
	v_mul_f32_e32 v2, 0x41800000, v2
	v_cvt_pk_fp8_f32 v38, v1, v2 op_sel:[0,0,1]
	v_lshlrev_b32_e32 v1, 16, v28
	v_and_b32_e32 v2, 0xffff0000, v28
	v_mul_f32_e32 v1, 0x41800000, v1
	v_mul_f32_e32 v2, 0x41800000, v2
	v_mov_b32_e32 v28, 0
	v_cvt_pk_fp8_f32 v28, v1, v2
	v_mul_f32_e32 v3, 0x41800000, v3
	v_mul_f32_e32 v32, 0x41800000, v32
	v_cvt_pk_fp8_f32 v33, v3, v32 op_sel:[0,0,1]
	v_lshlrev_b32_e32 v3, 16, v29
	v_and_b32_e32 v2, 0xffff0000, v29
	v_mul_f32_e32 v1, 0x41800000, v3
	v_mul_f32_e32 v2, 0x41800000, v2
	v_cvt_pk_fp8_f32 v28, v1, v2 op_sel:[0,0,1]
	v_lshlrev_b32_e32 v1, 16, v30
	v_and_b32_e32 v2, 0xffff0000, v30
	v_mul_f32_e32 v1, 0x41800000, v1
	v_mul_f32_e32 v2, 0x41800000, v2
	v_mov_b32_e32 v29, 0
	v_cvt_pk_fp8_f32 v29, v1, v2
	v_lshlrev_b32_e32 v3, 16, v31
	v_and_b32_e32 v2, 0xffff0000, v31
	v_mul_f32_e32 v1, 0x41800000, v3
	v_mul_f32_e32 v2, 0x41800000, v2
	v_cvt_pk_fp8_f32 v29, v1, v2 op_sel:[0,0,1]
	v_lshlrev_b32_e32 v1, 16, v24
	v_and_b32_e32 v2, 0xffff0000, v24
	v_mul_f32_e32 v1, 0x41800000, v1
	v_mul_f32_e32 v2, 0x41800000, v2
	v_lshlrev_b32_e32 v3, 16, v25
	v_and_b32_e32 v24, 0xffff0000, v25
	v_mov_b32_e32 v25, 0
	v_cvt_pk_fp8_f32 v25, v1, v2
	v_lshlrev_b32_e32 v1, 16, v26
	v_and_b32_e32 v2, 0xffff0000, v26
	v_mul_f32_e32 v1, 0x41800000, v1
	v_mul_f32_e32 v2, 0x41800000, v2
	v_mov_b32_e32 v30, 0
	v_cvt_pk_fp8_f32 v30, v1, v2
	v_lshlrev_b32_e32 v26, 16, v27
	v_and_b32_e32 v2, 0xffff0000, v27
	v_mul_f32_e32 v3, 0x41800000, v3
	v_mul_f32_e32 v24, 0x41800000, v24
	v_mul_f32_e32 v1, 0x41800000, v26
	v_mul_f32_e32 v2, 0x41800000, v2
	v_cvt_pk_fp8_f32 v30, v1, v2 op_sel:[0,0,1]
	v_cvt_pk_fp8_f32 v25, v3, v24 op_sel:[0,0,1]
	v_mov_b32_e32 v2, v0
	v_mov_b32_e32 v3, v0
	v_cndmask_b32_e64 v131, 0, v37, s[6:7]
	v_cndmask_b32_e64 v130, 0, v36, s[6:7]
	v_cndmask_b32_e64 v133, 0, v38, s[6:7]
	v_cndmask_b32_e64 v132, 0, v33, s[6:7]
	v_cndmask_b32_e64 v135, 0, v29, s[6:7]
	v_cndmask_b32_e64 v134, 0, v28, s[6:7]
	v_cndmask_b32_e64 v137, 0, v30, s[6:7]
	v_cndmask_b32_e64 v136, 0, v25, s[6:7]
	v_mov_b32_e32 v1, v0
	v_mov_b64_e32 v[54:55], v[2:3]
	v_mov_b64_e32 v[50:51], v[2:3]
	v_mov_b64_e32 v[46:47], v[2:3]
	v_mov_b64_e32 v[42:43], v[2:3]
	v_mov_b64_e32 v[38:39], v[2:3]
	v_mov_b64_e32 v[34:35], v[2:3]
	v_mov_b64_e32 v[30:31], v[2:3]
	v_mov_b64_e32 v[26:27], v[2:3]
	s_mov_b32 s20, 0
	s_sub_i32 s21, s45, 63
	v_mov_b32_e32 v129, 0
	v_mov_b32_e32 v161, 0xf149f2ca
	v_mov_b64_e32 v[52:53], v[0:1]
	v_mov_b64_e32 v[48:49], v[0:1]
	v_mov_b64_e32 v[44:45], v[0:1]
	v_mov_b64_e32 v[40:41], v[0:1]
	v_mov_b64_e32 v[36:37], v[0:1]
	v_mov_b64_e32 v[32:33], v[0:1]
	v_mov_b64_e32 v[28:29], v[0:1]
	v_mov_b64_e32 v[24:25], v[0:1]
	s_mov_b32 s48, 0
	s_mov_b64 s[70:71], 0
	s_mov_b64 s[76:77], 0
	s_mov_b64 s[84:85], 0
	s_mov_b64 s[88:89], 0
	s_mov_b64 s[98:99], 0
	s_mov_b64 s[16:17], s[62:63]
	v_readlane_b32 s8, v181, 0
	v_readlane_b32 s9, v181, 1
	v_readlane_b32 s10, v181, 8
	v_readlane_b32 s11, v181, 9
	v_readlane_b32 s12, v181, 16
	v_readlane_b32 s13, v181, 17
	v_readlane_b32 s14, v181, 24
	v_readlane_b32 s15, v181, 25
.Lx_bit0:
	s_cmp_eq_u64 s[16:17], 0
	s_cbranch_scc1 .Lx_bitend0
	s_ff1_i32_b64 s18, s[16:17]
	s_lshl_b32 s19, s18, 2
	s_add_i32 s19, s19, 0
	s_mov_b32 m0, s48
	s_or_b32 s22, s18, 0x10000
	v_writelane_b32 v183, s19, m0
	s_bfe_u64 s[24:25], s[8:9], s22
	s_bfe_u64 s[26:27], s[10:11], s22
	s_bfe_u64 s[28:29], s[12:13], s22
	s_bfe_u64 s[34:35], s[14:15], s22
	s_and_b64 s[36:37], s[24:25], s[26:27]
	s_and_b64 s[38:39], s[28:29], s[34:35]
	s_and_b64 s[36:37], s[36:37], s[38:39]
	s_lshl_b64 s[24:25], s[24:25], s48
	s_lshl_b64 s[26:27], s[26:27], s48
	s_lshl_b64 s[28:29], s[28:29], s48
	s_lshl_b64 s[34:35], s[34:35], s48
	s_lshl_b64 s[36:37], s[36:37], s48
	s_or_b64 s[70:71], s[70:71], s[24:25]
	s_or_b64 s[76:77], s[76:77], s[26:27]
	s_or_b64 s[84:85], s[84:85], s[28:29]
	s_or_b64 s[88:89], s[88:89], s[34:35]
	s_or_b64 s[98:99], s[98:99], s[36:37]
	s_add_i32 s48, s48, 1
	s_add_u32 s18, s16, -1
	s_addc_u32 s19, s17, -1
	s_and_b64 s[16:17], s[16:17], s[18:19]
	s_branch .Lx_bit0
.Lx_bitend0:
	s_mov_b64 s[16:17], s[64:65]
	v_readlane_b32 s8, v181, 2
	v_readlane_b32 s9, v181, 3
	v_readlane_b32 s10, v181, 10
	v_readlane_b32 s11, v181, 11
	v_readlane_b32 s12, v181, 18
	v_readlane_b32 s13, v181, 19
	v_readlane_b32 s14, v181, 26
	v_readlane_b32 s15, v181, 27
.Lx_bit1:
	s_cmp_eq_u64 s[16:17], 0
	s_cbranch_scc1 .Lx_bitend1
	s_ff1_i32_b64 s18, s[16:17]
	s_lshl_b32 s19, s18, 2
	s_add_i32 s19, s19, 1
	s_mov_b32 m0, s48
	s_or_b32 s22, s18, 0x10000
	v_writelane_b32 v183, s19, m0
	s_bfe_u64 s[24:25], s[8:9], s22
	s_bfe_u64 s[26:27], s[10:11], s22
	s_bfe_u64 s[28:29], s[12:13], s22
	s_bfe_u64 s[34:35], s[14:15], s22
	s_and_b64 s[36:37], s[24:25], s[26:27]
	s_and_b64 s[38:39], s[28:29], s[34:35]
	s_and_b64 s[36:37], s[36:37], s[38:39]
	s_lshl_b64 s[24:25], s[24:25], s48
	s_lshl_b64 s[26:27], s[26:27], s48
	s_lshl_b64 s[28:29], s[28:29], s48
	s_lshl_b64 s[34:35], s[34:35], s48
	s_lshl_b64 s[36:37], s[36:37], s48
	s_or_b64 s[70:71], s[70:71], s[24:25]
	s_or_b64 s[76:77], s[76:77], s[26:27]
	s_or_b64 s[84:85], s[84:85], s[28:29]
	s_or_b64 s[88:89], s[88:89], s[34:35]
	s_or_b64 s[98:99], s[98:99], s[36:37]
	s_add_i32 s48, s48, 1
	s_add_u32 s18, s16, -1
	s_addc_u32 s19, s17, -1
	s_and_b64 s[16:17], s[16:17], s[18:19]
	s_branch .Lx_bit1
.Lx_bitend1:
	s_mov_b64 s[16:17], s[66:67]
	v_readlane_b32 s8, v181, 4
	v_readlane_b32 s9, v181, 5
	v_readlane_b32 s10, v181, 12
	v_readlane_b32 s11, v181, 13
	v_readlane_b32 s12, v181, 20
	v_readlane_b32 s13, v181, 21
	v_readlane_b32 s14, v181, 28
	v_readlane_b32 s15, v181, 29
.Lx_bit2:
	s_cmp_eq_u64 s[16:17], 0
	s_cbranch_scc1 .Lx_bitend2
	s_ff1_i32_b64 s18, s[16:17]
	s_lshl_b32 s19, s18, 2
	s_add_i32 s19, s19, 2
	s_mov_b32 m0, s48
	s_or_b32 s22, s18, 0x10000
	v_writelane_b32 v183, s19, m0
	s_bfe_u64 s[24:25], s[8:9], s22
	s_bfe_u64 s[26:27], s[10:11], s22
	s_bfe_u64 s[28:29], s[12:13], s22
	s_bfe_u64 s[34:35], s[14:15], s22
	s_and_b64 s[36:37], s[24:25], s[26:27]
	s_and_b64 s[38:39], s[28:29], s[34:35]
	s_and_b64 s[36:37], s[36:37], s[38:39]
	s_lshl_b64 s[24:25], s[24:25], s48
	s_lshl_b64 s[26:27], s[26:27], s48
	s_lshl_b64 s[28:29], s[28:29], s48
	s_lshl_b64 s[34:35], s[34:35], s48
	s_lshl_b64 s[36:37], s[36:37], s48
	s_or_b64 s[70:71], s[70:71], s[24:25]
	s_or_b64 s[76:77], s[76:77], s[26:27]
	s_or_b64 s[84:85], s[84:85], s[28:29]
	s_or_b64 s[88:89], s[88:89], s[34:35]
	s_or_b64 s[98:99], s[98:99], s[36:37]
	s_add_i32 s48, s48, 1
	s_add_u32 s18, s16, -1
	s_addc_u32 s19, s17, -1
	s_and_b64 s[16:17], s[16:17], s[18:19]
	s_branch .Lx_bit2
.Lx_bitend2:
	s_mov_b64 s[16:17], s[68:69]
	v_readlane_b32 s8, v181, 6
	v_readlane_b32 s9, v181, 7
	v_readlane_b32 s10, v181, 14
	v_readlane_b32 s11, v181, 15
	v_readlane_b32 s12, v181, 22
	v_readlane_b32 s13, v181, 23
	v_readlane_b32 s14, v181, 30
	v_readlane_b32 s15, v181, 31
.Lx_bit3:
	s_cmp_eq_u64 s[16:17], 0
	s_cbranch_scc1 .Lx_bitend3
	s_ff1_i32_b64 s18, s[16:17]
	s_lshl_b32 s19, s18, 2
	s_add_i32 s19, s19, 3
	s_mov_b32 m0, s48
	s_or_b32 s22, s18, 0x10000
	v_writelane_b32 v183, s19, m0
	s_bfe_u64 s[24:25], s[8:9], s22
	s_bfe_u64 s[26:27], s[10:11], s22
	s_bfe_u64 s[28:29], s[12:13], s22
	s_bfe_u64 s[34:35], s[14:15], s22
	s_and_b64 s[36:37], s[24:25], s[26:27]
	s_and_b64 s[38:39], s[28:29], s[34:35]
	s_and_b64 s[36:37], s[36:37], s[38:39]
	s_lshl_b64 s[24:25], s[24:25], s48
	s_lshl_b64 s[26:27], s[26:27], s48
	s_lshl_b64 s[28:29], s[28:29], s48
	s_lshl_b64 s[34:35], s[34:35], s48
	s_lshl_b64 s[36:37], s[36:37], s48
	s_or_b64 s[70:71], s[70:71], s[24:25]
	s_or_b64 s[76:77], s[76:77], s[26:27]
	s_or_b64 s[84:85], s[84:85], s[28:29]
	s_or_b64 s[88:89], s[88:89], s[34:35]
	s_or_b64 s[98:99], s[98:99], s[36:37]
	s_add_i32 s48, s48, 1
	s_add_u32 s18, s16, -1
	s_addc_u32 s19, s17, -1
	s_and_b64 s[16:17], s[16:17], s[18:19]
	s_branch .Lx_bit3
.Lx_bitend3:
	s_mov_b32 exec_lo, 0x000f000f
	s_mov_b32 exec_hi, 0x000f000f
	v_mov_b32_e32 v232, s70
	v_mov_b32_e32 v233, s71
	s_mov_b32 exec_lo, 0x00f000f0
	s_mov_b32 exec_hi, 0x00f000f0
	v_mov_b32_e32 v232, s76
	v_mov_b32_e32 v233, s77
	s_mov_b32 exec_lo, 0x0f000f00
	s_mov_b32 exec_hi, 0x0f000f00
	v_mov_b32_e32 v232, s84
	v_mov_b32_e32 v233, s85
	s_mov_b32 exec_lo, 0xf000f000
	s_mov_b32 exec_hi, 0xf000f000
	v_mov_b32_e32 v232, s88
	v_mov_b32_e32 v233, s89
	s_mov_b64 exec, -1
	s_mov_b32 s47, 0
	s_nop 0
	v_readlane_b32 s50, v183, 0
	ds_read_b128 v[184:187], v180
	ds_read_b128 v[188:191], v180 offset:2048
	ds_read_b128 v[192:195], v180 offset:4096
	ds_read_b128 v[196:199], v180 offset:6144
	ds_read_b128 v[200:203], v180 offset:1024
	ds_read_b128 v[204:207], v180 offset:3072
	ds_read_b128 v[208:211], v180 offset:5120
	ds_read_b128 v[212:215], v180 offset:7168
	ds_read_b128 v[216:219], v180 offset:8192
	ds_read_b128 v[220:223], v180 offset:9216
	ds_read_b128 v[224:227], v180 offset:10240
	ds_read_b128 v[228:231], v180 offset:11264
	ds_read_b128 v[236:239], v180 offset:12288
	ds_read_b128 v[240:243], v180 offset:13312
	ds_read_b128 v[244:247], v180 offset:14336
	ds_read_b128 v[248:251], v180 offset:15360
	s_waitcnt lgkmcnt(0)
.Lsl_loop:
	s_add_i32 s32, s47, 0
	s_add_i32 s47, s47, 1
	s_cmp_lt_u32 s47, s48
	s_cselect_b32 s49, 1, 0
	s_cselect_b32 s56, s47, 0
	s_mov_b32 m0, s56
	s_nop 0
	v_readlane_b32 s51, v183, m0
	s_ashr_i32 s57, s51, 31
	s_mov_b32 s56, s51
	s_lshl_b64 s[52:53], s[56:57], 13
	s_add_u32 s52, s52, s41
	s_addc_u32 s53, s53, 0
	s_add_u32 s54, s52, 0x1000
	s_addc_u32 s55, s53, 0
	v_lshl_add_u64 v[172:173], v[112:113], 0, s[52:53]
	v_lshl_add_u64 v[174:175], v[112:113], 0, s[54:55]
	s_waitcnt vmcnt(15)
	v_mfma_f32_16x16x32_fp8_fp8 v[76:79], v[184:185], v[130:131], 0
	s_waitcnt vmcnt(14)
	v_mfma_f32_16x16x32_fp8_fp8 v[80:83], v[188:189], v[130:131], 0
	v_mfma_f32_16x16x32_fp8_fp8 v[56:59], v[186:187], v[132:133], v[76:79]
	s_waitcnt vmcnt(13)
	v_mfma_f32_16x16x32_fp8_fp8 v[94:97], v[192:193], v[130:131], 0
	s_waitcnt vmcnt(12)
	v_mfma_f32_16x16x32_fp8_fp8 v[98:101], v[196:197], v[130:131], 0
	v_mfma_f32_16x16x32_fp8_fp8 v[60:63], v[190:191], v[132:133], v[80:83]
	s_waitcnt vmcnt(11)
	v_mfma_f32_16x16x32_fp8_fp8 v[56:59], v[200:201], v[134:135], v[56:59]
	v_mfma_f32_16x16x32_fp8_fp8 v[64:67], v[194:195], v[132:133], v[94:97]
	v_mfma_f32_16x16x32_fp8_fp8 v[68:71], v[198:199], v[132:133], v[98:101]
	s_waitcnt vmcnt(10)
	v_mfma_f32_16x16x32_fp8_fp8 v[60:63], v[204:205], v[134:135], v[60:63]
	v_mfma_f32_16x16x32_fp8_fp8 v[100:103], v[202:203], v[136:137], v[56:59]
	s_waitcnt vmcnt(9)
	v_mfma_f32_16x16x32_fp8_fp8 v[142:145], v[208:209], v[134:135], v[64:67]
	s_waitcnt vmcnt(8)
	v_mfma_f32_16x16x32_fp8_fp8 v[146:149], v[212:213], v[134:135], v[68:71]
	v_mfma_f32_16x16x32_fp8_fp8 v[96:99], v[206:207], v[136:137], v[60:63]
	v_mfma_f32_16x16x32_fp8_fp8 v[92:95], v[210:211], v[136:137], v[142:145]
	v_mfma_f32_16x16x32_fp8_fp8 v[88:91], v[214:215], v[136:137], v[146:149]
	s_cmp_eq_u32 s49, 0
	s_cbranch_scc1 .Lsl_nopf
	global_load_dwordx4 v[184:187], v[172:173], off
	global_load_dwordx4 v[188:191], v[172:173], off offset:2048
	global_load_dwordx4 v[192:195], v[174:175], off
	global_load_dwordx4 v[196:199], v[174:175], off offset:2048
	global_load_dwordx4 v[200:203], v[172:173], off offset:1024
	global_load_dwordx4 v[204:207], v[172:173], off offset:3072
	global_load_dwordx4 v[208:211], v[174:175], off offset:1024
	global_load_dwordx4 v[212:215], v[174:175], off offset:3072
.Lsl_nopf:
	s_lshl_b32 s22, s50, 6
	s_sub_i32 s18, s21, s22
	s_cmpk_lt_i32 s18, 0x7f
	s_cbranch_scc0 .Lsl_far
	s_sub_i32 s18, 0, s22
	s_add_i32 s18, s18, s45
	v_sub_u32_e32 v1, s18, v155
	v_add_u32_e32 v140, s18, v156
	v_sub_u32_e32 v141, s18, v105
	v_sub_u32_e32 v146, s18, v116
	v_sub_u32_e32 v149, s18, v119
	v_sub_u32_e32 v150, s18, v120
	v_med3_i32 v2, v1, 0, v159
	v_med3_i32 v3, v140, 0, v159
	v_med3_i32 v138, v146, 0, v159
	v_med3_i32 v139, v141, 0, v159
	v_sub_u32_e32 v147, s18, v117
	v_sub_u32_e32 v148, s18, v118
	v_med3_i32 v144, v150, 0, v159
	v_med3_i32 v145, v149, 0, v159
	v_lshl_add_u32 v2, v2, 2, v154
	v_lshl_add_u32 v3, v3, 2, v154
	v_lshl_add_u32 v138, v138, 2, v154
	v_lshl_add_u32 v139, v139, 2, v154
	v_med3_i32 v142, v148, 0, v159
	v_med3_i32 v143, v147, 0, v159
	v_lshl_add_u32 v144, v144, 2, v154
	v_lshl_add_u32 v145, v145, 2, v154
	v_lshl_add_u32 v142, v142, 2, v154
	v_lshl_add_u32 v143, v143, 2, v154
	ds_read_b32 v151, v2
	ds_read_b32 v162, v3
	ds_read_b32 v2, v138
	ds_read_b32 v3, v139
	ds_read_b32 v138, v142
	ds_read_b32 v139, v143
	ds_read_b32 v144, v144
	ds_read_b32 v145, v145
	s_waitcnt lgkmcnt(7)
	v_fmac_f32_e32 v151, 0x3d800000, v100
	v_cmp_lt_i32_e32 vcc, -1, v1
	s_waitcnt lgkmcnt(6)
	v_fmac_f32_e32 v162, 0x3d800000, v101
	s_waitcnt lgkmcnt(4)
	v_pk_fma_f32 v[2:3], v[102:103], s[2:3], v[2:3] op_sel_hi:[1,0,1]
	v_cndmask_b32_e32 v142, v160, v151, vcc
	v_cmp_lt_i32_e32 vcc, -1, v140
	v_subrev_u32_e32 v168, 37, v1
	v_subrev_u32_e32 v166, 35, v1
	v_cndmask_b32_e32 v143, v160, v162, vcc
	v_cmp_lt_i32_e32 vcc, -1, v141
	v_max3_f32 v151, v142, s40, v143
	v_subrev_u32_e32 v167, 34, v1
	v_cndmask_b32_e32 v141, v160, v3, vcc
	v_cmp_lt_i32_e32 vcc, -1, v146
	v_subrev_u32_e32 v169, 36, v1
	v_med3_i32 v162, v168, 0, v159
	v_cndmask_b32_e32 v140, v160, v2, vcc
	s_waitcnt lgkmcnt(2)
	v_pk_fma_f32 v[2:3], v[96:97], s[2:3], v[138:139] op_sel_hi:[1,0,1]
	v_cmp_lt_i32_e32 vcc, -1, v147
	v_max3_f32 v146, v151, v140, v141
	v_subrev_u32_e32 v170, 39, v1
	v_cndmask_b32_e32 v139, v160, v3, vcc
	v_cmp_lt_i32_e32 vcc, -1, v148
	v_lshl_add_u32 v163, v162, 2, v154
	v_med3_i32 v147, v166, 0, v159
	v_cndmask_b32_e32 v138, v160, v2, vcc
	s_waitcnt lgkmcnt(0)
	v_pk_fma_f32 v[2:3], v[98:99], s[2:3], v[144:145] op_sel_hi:[1,0,1]
	v_cmp_lt_i32_e32 vcc, -1, v149
	v_subrev_u32_e32 v149, 33, v1
	v_max3_f32 v146, v146, v138, v139
	v_cndmask_b32_e32 v3, v160, v3, vcc
	v_cmp_lt_i32_e32 vcc, -1, v150
	v_subrev_u32_e32 v150, 32, v1
	v_subrev_u32_e32 v1, 38, v1
	v_cndmask_b32_e32 v2, v160, v2, vcc
	v_med3_i32 v162, v1, 0, v159
	v_max3_f32 v148, v146, v2, v3
	v_med3_i32 v144, v150, 0, v159
	v_med3_i32 v145, v149, 0, v159
	v_med3_i32 v146, v167, 0, v159
	v_lshl_add_u32 v164, v162, 2, v154
	v_med3_i32 v162, v170, 0, v159
	v_lshl_add_u32 v144, v144, 2, v154
	v_lshl_add_u32 v145, v145, 2, v154
	v_lshl_add_u32 v146, v146, 2, v154
	v_lshl_add_u32 v147, v147, 2, v154
	v_med3_i32 v151, v169, 0, v159
	v_lshl_add_u32 v165, v162, 2, v154
	v_lshl_add_u32 v151, v151, 2, v154
	ds_read_b32 v144, v144
	ds_read_b32 v145, v145
	ds_read_b32 v146, v146
	ds_read_b32 v147, v147
	ds_read_b32 v162, v151
	ds_read_b32 v163, v163
	ds_read_b32 v164, v164
	ds_read_b32 v165, v165
	s_waitcnt lgkmcnt(6)
	v_pk_fma_f32 v[144:145], v[92:93], s[2:3], v[144:145] op_sel_hi:[1,0,1]
	v_cmp_lt_i32_e32 vcc, -1, v149
	s_nop 0
	v_cndmask_b32_e32 v151, v160, v145, vcc
	v_cmp_lt_i32_e32 vcc, -1, v150
	s_nop 1
	v_cndmask_b32_e32 v150, v160, v144, vcc
	s_waitcnt lgkmcnt(4)
	v_pk_fma_f32 v[144:145], v[94:95], s[2:3], v[146:147] op_sel_hi:[1,0,1]
	v_cmp_lt_i32_e32 vcc, -1, v166
	v_max3_f32 v171, v148, v150, v151
	s_nop 0
	v_cndmask_b32_e32 v149, v160, v145, vcc
	v_cmp_lt_i32_e32 vcc, -1, v167
	s_nop 1
	v_cndmask_b32_e32 v148, v160, v144, vcc
	s_waitcnt lgkmcnt(2)
	v_pk_fma_f32 v[144:145], v[88:89], s[2:3], v[162:163] op_sel_hi:[1,0,1]
	v_cmp_lt_i32_e32 vcc, -1, v168
	v_max3_f32 v166, v171, v148, v149
	s_nop 0
	v_cndmask_b32_e32 v147, v160, v145, vcc
	v_cmp_lt_i32_e32 vcc, -1, v169
	s_nop 1
	v_cndmask_b32_e32 v146, v160, v144, vcc
	s_waitcnt lgkmcnt(0)
	v_pk_fma_f32 v[144:145], v[90:91], s[2:3], v[164:165] op_sel_hi:[1,0,1]
	v_cmp_lt_i32_e32 vcc, -1, v170
	v_max3_f32 v162, v166, v146, v147
	s_nop 0
	v_cndmask_b32_e32 v145, v160, v145, vcc
	v_cmp_lt_i32_e32 vcc, -1, v1
	s_nop 1
	v_cndmask_b32_e32 v144, v160, v144, vcc
	v_max3_f32 v1, v162, v144, v145
	s_bitcmp1_b64 s[98:99], s32
	s_cbranch_scc1 .Lsl_sm
	v_lshrrev_b64 v[56:57], s32, v[232:233]
	v_and_b32_e32 v56, 1, v56
	v_cmp_eq_u32_e32 vcc, 1, v56
	s_nop 1
	v_cndmask_b32_e32 v142, v160, v142, vcc
	v_cndmask_b32_e32 v143, v160, v143, vcc
	v_cndmask_b32_e32 v140, v160, v140, vcc
	v_cndmask_b32_e32 v141, v160, v141, vcc
	v_cndmask_b32_e32 v138, v160, v138, vcc
	v_cndmask_b32_e32 v139, v160, v139, vcc
	v_cndmask_b32_e32 v2, v160, v2, vcc
	v_cndmask_b32_e32 v3, v160, v3, vcc
	v_cndmask_b32_e32 v150, v160, v150, vcc
	v_cndmask_b32_e32 v151, v160, v151, vcc
	v_cndmask_b32_e32 v148, v160, v148, vcc
	v_cndmask_b32_e32 v149, v160, v149, vcc
	v_cndmask_b32_e32 v146, v160, v146, vcc
	v_cndmask_b32_e32 v147, v160, v147, vcc
	v_cndmask_b32_e32 v144, v160, v144, vcc
	v_cndmask_b32_e32 v145, v160, v145, vcc
	v_max3_f32 v1, v142, s40, v143
	v_max3_f32 v1, v1, v140, v141
	v_max3_f32 v1, v1, v138, v139
	v_max3_f32 v1, v1, v2, v3
	v_max3_f32 v1, v1, v150, v151
	v_max3_f32 v1, v1, v148, v149
	v_max3_f32 v1, v1, v146, v147
	v_max3_f32 v1, v1, v144, v145
	s_branch .Lsl_sm
.Lsl_far:
	v_lshrrev_b64 v[56:57], s32, v[232:233]
	v_and_b32_e32 v56, 1, v56
	v_cmp_eq_u32_e32 vcc, 1, v56
	s_nop 1
	v_cndmask_b32_e32 v58, v160, v110, vcc
	v_mov_b32_e32 v59, v58
	v_pk_fma_f32 v[142:143], v[100:101], s[2:3], v[58:59] op_sel_hi:[1,0,1]
	v_pk_fma_f32 v[140:141], v[102:103], s[2:3], v[58:59] op_sel_hi:[1,0,1]
	v_max3_f32 v1, v142, s40, v143
	v_max3_f32 v1, v1, v140, v141
	v_pk_fma_f32 v[138:139], v[96:97], s[2:3], v[58:59] op_sel_hi:[1,0,1]
	v_pk_fma_f32 v[2:3], v[98:99], s[2:3], v[58:59] op_sel_hi:[1,0,1]
	v_max3_f32 v1, v1, v138, v139
	v_max3_f32 v1, v1, v2, v3
	v_pk_fma_f32 v[150:151], v[92:93], s[2:3], v[58:59] op_sel_hi:[1,0,1]
	v_pk_fma_f32 v[148:149], v[94:95], s[2:3], v[58:59] op_sel_hi:[1,0,1]
	v_max3_f32 v1, v1, v150, v151
	v_max3_f32 v1, v1, v148, v149
	v_pk_fma_f32 v[146:147], v[88:89], s[2:3], v[58:59] op_sel_hi:[1,0,1]
	v_pk_fma_f32 v[144:145], v[90:91], s[2:3], v[58:59] op_sel_hi:[1,0,1]
	v_max3_f32 v1, v1, v146, v147
	v_max3_f32 v1, v1, v144, v145
.Lsl_sm:
	v_mov_b32_e32 v88, v1
	s_nop 1
	v_permlane32_swap_b32_e32 v1, v88
	v_max_f32_e32 v1, v1, v88
	v_mov_b32_e32 v88, v1
	s_nop 1
	v_permlane16_swap_b32_e32 v1, v88
	v_max3_f32 v1, v161, v1, v88
	v_sub_f32_e32 v88, v161, v1
	v_sub_f32_e32 v142, v142, v1
	v_sub_f32_e32 v143, v143, v1
	v_sub_f32_e32 v140, v140, v1
	v_sub_f32_e32 v141, v141, v1
	v_exp_f32_e32 v88, v88
	v_exp_f32_e32 v142, v142
	v_sub_f32_e32 v138, v138, v1
	v_exp_f32_e32 v143, v143
	v_sub_f32_e32 v139, v139, v1
	v_exp_f32_e32 v140, v140
	v_sub_f32_e32 v2, v2, v1
	v_exp_f32_e32 v141, v141
	v_sub_f32_e32 v3, v3, v1
	v_exp_f32_e32 v138, v138
	v_sub_f32_e32 v150, v150, v1
	v_exp_f32_e32 v139, v139
	v_sub_f32_e32 v151, v151, v1
	v_exp_f32_e32 v2, v2
	v_sub_f32_e32 v148, v148, v1
	v_exp_f32_e32 v3, v3
	v_sub_f32_e32 v149, v149, v1
	v_exp_f32_e32 v150, v150
	v_sub_f32_e32 v146, v146, v1
	v_exp_f32_e32 v151, v151
	v_sub_f32_e32 v147, v147, v1
	v_exp_f32_e32 v148, v148
	v_sub_f32_e32 v144, v144, v1
	v_exp_f32_e32 v149, v149
	v_sub_f32_e32 v145, v145, v1
	v_exp_f32_e32 v146, v146
	v_exp_f32_e32 v147, v147
	v_exp_f32_e32 v144, v144
	v_exp_f32_e32 v145, v145
	v_mov_b32_e32 v161, v1
	v_mul_f32_e32 v56, 0x42800000, v142
	v_mul_f32_e32 v57, 0x42800000, v143
	v_mul_f32_e32 v58, 0x42800000, v140
	v_mul_f32_e32 v59, 0x42800000, v141
	v_mul_f32_e32 v60, 0x42800000, v138
	v_mul_f32_e32 v61, 0x42800000, v139
	v_mul_f32_e32 v62, 0x42800000, v2
	v_mul_f32_e32 v63, 0x42800000, v3
	v_mul_f32_e32 v64, 0x42800000, v150
	v_mul_f32_e32 v65, 0x42800000, v151
	v_mul_f32_e32 v66, 0x42800000, v148
	v_mul_f32_e32 v67, 0x42800000, v149
	v_mul_f32_e32 v68, 0x42800000, v146
	v_mul_f32_e32 v69, 0x42800000, v147
	v_mul_f32_e32 v70, 0x42800000, v144
	v_mul_f32_e32 v71, 0x42800000, v145
	v_pk_mul_f32 v[42:43], v[42:43], v[88:89] op_sel_hi:[1,0]
	v_pk_mul_f32 v[40:41], v[40:41], v[88:89] op_sel_hi:[1,0]
	v_pk_mul_f32 v[38:39], v[38:39], v[88:89] op_sel_hi:[1,0]
	v_pk_mul_f32 v[36:37], v[36:37], v[88:89] op_sel_hi:[1,0]
	v_pk_mul_f32 v[34:35], v[34:35], v[88:89] op_sel_hi:[1,0]
	v_pk_mul_f32 v[32:33], v[32:33], v[88:89] op_sel_hi:[1,0]
	v_pk_mul_f32 v[30:31], v[30:31], v[88:89] op_sel_hi:[1,0]
	v_pk_mul_f32 v[28:29], v[28:29], v[88:89] op_sel_hi:[1,0]
	v_cvt_pk_fp8_f32 v72, v56, v57
	v_cvt_pk_fp8_f32 v73, v60, v61
	v_cvt_pk_fp8_f32 v72, v58, v59 op_sel:[0,0,1]
	v_cvt_pk_fp8_f32 v73, v62, v63 op_sel:[0,0,1]
	v_pk_mul_f32 v[54:55], v[54:55], v[88:89] op_sel_hi:[1,0]
	v_pk_mul_f32 v[52:53], v[52:53], v[88:89] op_sel_hi:[1,0]
	v_pk_mul_f32 v[50:51], v[50:51], v[88:89] op_sel_hi:[1,0]
	v_pk_mul_f32 v[48:49], v[48:49], v[88:89] op_sel_hi:[1,0]
	v_pk_mul_f32 v[46:47], v[46:47], v[88:89] op_sel_hi:[1,0]
	v_pk_mul_f32 v[44:45], v[44:45], v[88:89] op_sel_hi:[1,0]
	v_pk_mul_f32 v[26:27], v[26:27], v[88:89] op_sel_hi:[1,0]
	v_pk_mul_f32 v[24:25], v[24:25], v[88:89] op_sel_hi:[1,0]
	v_cvt_pk_fp8_f32 v74, v64, v65
	v_cvt_pk_fp8_f32 v75, v68, v69
	v_cvt_pk_fp8_f32 v74, v66, v67 op_sel:[0,0,1]
	v_cvt_pk_fp8_f32 v75, v70, v71 op_sel:[0,0,1]
	v_add_f32_e32 v76, v142, v143
	v_add_f32_e32 v76, v140, v76
	v_add_f32_e32 v76, v141, v76
	v_add_f32_e32 v76, v138, v76
	v_add_f32_e32 v76, v139, v76
	v_add_f32_e32 v76, v2, v76
	v_add_f32_e32 v76, v3, v76
	v_add_f32_e32 v76, v150, v76
	v_add_f32_e32 v76, v151, v76
	v_add_f32_e32 v76, v148, v76
	v_add_f32_e32 v76, v149, v76
	v_add_f32_e32 v76, v146, v76
	v_add_f32_e32 v76, v147, v76
	v_add_f32_e32 v76, v144, v76
	v_add_f32_e32 v76, v145, v76
	v_fmac_f32_e32 v76, v129, v88
	v_mov_b32_e32 v129, v76
	s_cmp_eq_u32 s49, 0
	s_cbranch_scc1 .Lsl_pv_last
	s_waitcnt vmcnt(12)
	v_mfma_f32_16x16x32_fp8_fp8 v[40:43], v[228:229], v[72:73], v[40:43]
	s_waitcnt vmcnt(11)
	v_mfma_f32_16x16x32_fp8_fp8 v[36:39], v[236:237], v[72:73], v[36:39]
	s_waitcnt vmcnt(10)
	v_mfma_f32_16x16x32_fp8_fp8 v[32:35], v[240:241], v[72:73], v[32:35]
	s_waitcnt vmcnt(9)
	v_mfma_f32_16x16x32_fp8_fp8 v[28:31], v[244:245], v[72:73], v[28:31]
	v_mfma_f32_16x16x32_fp8_fp8 v[52:55], v[216:217], v[72:73], v[52:55]
	v_mfma_f32_16x16x32_fp8_fp8 v[48:51], v[220:221], v[72:73], v[48:51]
	v_mfma_f32_16x16x32_fp8_fp8 v[44:47], v[224:225], v[72:73], v[44:47]
	s_waitcnt vmcnt(8)
	v_mfma_f32_16x16x32_fp8_fp8 v[24:27], v[248:249], v[72:73], v[24:27]
	v_mfma_f32_16x16x32_fp8_fp8 v[52:55], v[218:219], v[74:75], v[52:55]
	v_mfma_f32_16x16x32_fp8_fp8 v[48:51], v[222:223], v[74:75], v[48:51]
	v_mfma_f32_16x16x32_fp8_fp8 v[44:47], v[226:227], v[74:75], v[44:47]
	v_mfma_f32_16x16x32_fp8_fp8 v[40:43], v[230:231], v[74:75], v[40:43]
	v_mfma_f32_16x16x32_fp8_fp8 v[36:39], v[238:239], v[74:75], v[36:39]
	v_mfma_f32_16x16x32_fp8_fp8 v[32:35], v[242:243], v[74:75], v[32:35]
	v_mfma_f32_16x16x32_fp8_fp8 v[28:31], v[246:247], v[74:75], v[28:31]
	v_mfma_f32_16x16x32_fp8_fp8 v[24:27], v[250:251], v[74:75], v[24:27]
	v_lshl_add_u64 v[172:173], v[114:115], 0, s[52:53]
	v_lshl_add_u64 v[174:175], v[114:115], 0, s[54:55]
	global_load_dwordx4 v[216:219], v[172:173], off
	global_load_dwordx4 v[220:223], v[172:173], off offset:1024
	global_load_dwordx4 v[224:227], v[172:173], off offset:2048
	global_load_dwordx4 v[228:231], v[172:173], off offset:3072
	global_load_dwordx4 v[236:239], v[174:175], off
	global_load_dwordx4 v[240:243], v[174:175], off offset:1024
	global_load_dwordx4 v[244:247], v[174:175], off offset:2048
	global_load_dwordx4 v[248:251], v[174:175], off offset:3072
	s_mov_b32 s50, s51
	s_branch .Lsl_loop

	.amdhsa_kernel _Z10fwd_kernel4Args
		.amdhsa_group_segment_fixed_size 0
		.amdhsa_private_segment_fixed_size 0
		.amdhsa_kernarg_size 440
		.amdhsa_user_sgpr_count 2
		.amdhsa_user_sgpr_dispatch_ptr 0
		.amdhsa_user_sgpr_queue_ptr 0
		.amdhsa_user_sgpr_kernarg_segment_ptr 1
		.amdhsa_user_sgpr_dispatch_id 0
		.amdhsa_user_sgpr_kernarg_preload_length 0
		.amdhsa_user_sgpr_kernarg_preload_offset 0
		.amdhsa_user_sgpr_private_segment_size 0
		.amdhsa_uses_dynamic_stack 0
		.amdhsa_enable_private_segment 0
		.amdhsa_system_sgpr_workgroup_id_x 1
		.amdhsa_system_sgpr_workgroup_id_y 0
		.amdhsa_system_sgpr_workgroup_id_z 0
		.amdhsa_system_sgpr_workgroup_info 0
		.amdhsa_system_vgpr_workitem_id 2
		.amdhsa_next_free_vgpr 256
		.amdhsa_next_free_sgpr 100
		.amdhsa_accum_offset 256
		.amdhsa_reserve_vcc 1
		.amdhsa_float_round_mode_32 0
		.amdhsa_float_round_mode_16_64 0
		.amdhsa_float_denorm_mode_32 3
		.amdhsa_float_denorm_mode_16_64 3
		.amdhsa_dx10_clamp 1
		.amdhsa_ieee_mode 1
		.amdhsa_fp16_overflow 0
		.amdhsa_tg_split 0
		.amdhsa_exception_fp_ieee_invalid_op 0
		.amdhsa_exception_fp_denorm_src 0
		.amdhsa_exception_fp_ieee_div_zero 0
		.amdhsa_exception_fp_ieee_overflow 0
		.amdhsa_exception_fp_ieee_underflow 0
		.amdhsa_exception_fp_ieee_inexact 0
		.amdhsa_exception_int_div_zero 0
	.end_amdhsa_kernel

amdhsa.kernels:
  - .agpr_count:     0
    .args:
      - .offset:         0
        .size:           184
        .value_kind:     by_value
      - .offset:         184
        .size:           4
        .value_kind:     hidden_block_count_x
      - .offset:         188
        .size:           4
        .value_kind:     hidden_block_count_y
      - .offset:         192
        .size:           4
        .value_kind:     hidden_block_count_z
      - .offset:         196
        .size:           2
        .value_kind:     hidden_group_size_x
      - .offset:         198
        .size:           2
        .value_kind:     hidden_group_size_y
      - .offset:         200
        .size:           2
        .value_kind:     hidden_group_size_z
      - .offset:         202
        .size:           2
        .value_kind:     hidden_remainder_x
      - .offset:         204
        .size:           2
        .value_kind:     hidden_remainder_y
      - .offset:         206
        .size:           2
        .value_kind:     hidden_remainder_z
      - .offset:         224
        .size:           8
        .value_kind:     hidden_global_offset_x
      - .offset:         232
        .size:           8
        .value_kind:     hidden_global_offset_y
      - .offset:         240
        .size:           8
        .value_kind:     hidden_global_offset_z
      - .offset:         248
        .size:           2
        .value_kind:     hidden_grid_dims
      - .offset:         272
        .size:           8
        .value_kind:     hidden_multigrid_sync_arg
      - .offset:         304
        .size:           4
        .value_kind:     hidden_dynamic_lds_size
    .group_segment_fixed_size: 0
    .kernarg_segment_align: 8
    .kernarg_segment_size: 440
    .language:       OpenCL C
    .language_version:
      - 2
      - 0
    .max_flat_workgroup_size: 512
    .name:           _Z10fwd_kernel4Args
    .private_segment_fixed_size: 0
    .sgpr_count:     106
    .sgpr_spill_count: 88
    .symbol:         _Z10fwd_kernel4Args.kd
    .uniform_work_group_size: 1
    .uses_dynamic_stack: false
    .vgpr_count:     256
    .vgpr_spill_count: 0
    .wavefront_size: 64
